# adds: rb-chain workgroups lend 2 waves (not 7) to weight conversion; int8 scale loads issued before accumulator conversion; static prio for waves 4-7 in topk loop
# speedup vs baseline: 1.0202x; 1.0068x over previous
.LBB0_203:
	v_lshl_or_b32 v150, s48, 8, v173
	v_ashrrev_i32_e32 v151, 31, v150
	v_lshl_add_u32 v146, s24, 8, v171
	v_lshl_add_u64 v[190:191], v[150:151], 2, s[8:9]
	global_load_dwordx4 v[178:181], v[190:191], off
	v_ashrrev_i32_e32 v147, 31, v146
	v_lshl_add_u64 v[182:183], v[146:147], 2, s[6:7]
	global_load_dword v152, v[182:183], off
	global_load_dword v154, v[182:183], off offset:64
	global_load_dword v156, v[182:183], off offset:128
	v_add_u32_e32 v148, 0x80, v146
	v_ashrrev_i32_e32 v149, 31, v148
	v_lshl_add_u64 v[184:185], v[148:149], 2, s[6:7]
	global_load_dword v158, v[182:183], off offset:192
	global_load_dword v160, v[182:183], off offset:576
	global_load_dword v162, v[182:183], off offset:640
	global_load_dword v164, v[182:183], off offset:704
	global_load_dword v194, v[184:185], off
	s_nop 0
	global_load_dwordx4 v[182:185], v[190:191], off offset:16
	global_load_dwordx4 v[186:189], v[190:191], off offset:512
	s_nop 0
	global_load_dwordx4 v[190:193], v[190:191], off offset:528
	s_andn2_b64 vcc, exec, s[4:5]
	s_mov_b64 s[4:5], -1
	s_nop 15
	s_nop 15
	v_cvt_f32_i32 v126, v126
	v_cvt_f32_i32 v127, v127
	v_cvt_f32_i32 v128, v128
	v_cvt_f32_i32 v129, v129
	v_cvt_f32_i32 v114, v114
	v_cvt_f32_i32 v115, v115
	v_cvt_f32_i32 v116, v116
	v_cvt_f32_i32 v117, v117
	v_cvt_f32_i32 v122, v122
	v_cvt_f32_i32 v123, v123
	v_cvt_f32_i32 v124, v124
	v_cvt_f32_i32 v125, v125
	v_cvt_f32_i32 v106, v106
	v_cvt_f32_i32 v107, v107
	v_cvt_f32_i32 v108, v108
	v_cvt_f32_i32 v109, v109
	v_cvt_f32_i32 v118, v118
	v_cvt_f32_i32 v119, v119
	v_cvt_f32_i32 v120, v120
	v_cvt_f32_i32 v121, v121
	v_cvt_f32_i32 v102, v102
	v_cvt_f32_i32 v103, v103
	v_cvt_f32_i32 v104, v104
	v_cvt_f32_i32 v105, v105
	v_cvt_f32_i32 v110, v110
	v_cvt_f32_i32 v111, v111
	v_cvt_f32_i32 v112, v112
	v_cvt_f32_i32 v113, v113
	v_cvt_f32_i32 v98, v98
	v_cvt_f32_i32 v99, v99
	v_cvt_f32_i32 v100, v100
	v_cvt_f32_i32 v101, v101
	v_cvt_f32_i32 v86, v86
	v_cvt_f32_i32 v87, v87
	v_cvt_f32_i32 v88, v88
	v_cvt_f32_i32 v89, v89
	v_cvt_f32_i32 v46, v46
	v_cvt_f32_i32 v47, v47
	v_cvt_f32_i32 v48, v48
	v_cvt_f32_i32 v49, v49
	v_cvt_f32_i32 v70, v70
	v_cvt_f32_i32 v71, v71
	v_cvt_f32_i32 v72, v72
	v_cvt_f32_i32 v73, v73
	v_cvt_f32_i32 v42, v42
	v_cvt_f32_i32 v43, v43
	v_cvt_f32_i32 v44, v44
	v_cvt_f32_i32 v45, v45
	v_cvt_f32_i32 v62, v62
	v_cvt_f32_i32 v63, v63
	v_cvt_f32_i32 v64, v64
	v_cvt_f32_i32 v65, v65
	v_cvt_f32_i32 v34, v34
	v_cvt_f32_i32 v35, v35
	v_cvt_f32_i32 v36, v36
	v_cvt_f32_i32 v37, v37
	v_cvt_f32_i32 v54, v54
	v_cvt_f32_i32 v55, v55
	v_cvt_f32_i32 v56, v56
	v_cvt_f32_i32 v57, v57
	v_cvt_f32_i32 v26, v26
	v_cvt_f32_i32 v27, v27
	v_cvt_f32_i32 v28, v28
	v_cvt_f32_i32 v29, v29
	v_cvt_f32_i32 v94, v94
	v_cvt_f32_i32 v95, v95
	v_cvt_f32_i32 v96, v96
	v_cvt_f32_i32 v97, v97
	v_cvt_f32_i32 v78, v78
	v_cvt_f32_i32 v79, v79
	v_cvt_f32_i32 v80, v80
	v_cvt_f32_i32 v81, v81
	v_cvt_f32_i32 v90, v90
	v_cvt_f32_i32 v91, v91
	v_cvt_f32_i32 v92, v92
	v_cvt_f32_i32 v93, v93
	v_cvt_f32_i32 v66, v66
	v_cvt_f32_i32 v67, v67
	v_cvt_f32_i32 v68, v68
	v_cvt_f32_i32 v69, v69
	v_cvt_f32_i32 v82, v82
	v_cvt_f32_i32 v83, v83
	v_cvt_f32_i32 v84, v84
	v_cvt_f32_i32 v85, v85
	v_cvt_f32_i32 v58, v58
	v_cvt_f32_i32 v59, v59
	v_cvt_f32_i32 v60, v60
	v_cvt_f32_i32 v61, v61
	v_cvt_f32_i32 v74, v74
	v_cvt_f32_i32 v75, v75
	v_cvt_f32_i32 v76, v76
	v_cvt_f32_i32 v77, v77
	v_cvt_f32_i32 v50, v50
	v_cvt_f32_i32 v51, v51
	v_cvt_f32_i32 v52, v52
	v_cvt_f32_i32 v53, v53
	v_cvt_f32_i32 v38, v38
	v_cvt_f32_i32 v39, v39
	v_cvt_f32_i32 v40, v40
	v_cvt_f32_i32 v41, v41
	v_cvt_f32_i32 v14, v14
	v_cvt_f32_i32 v15, v15
	v_cvt_f32_i32 v16, v16
	v_cvt_f32_i32 v17, v17
	v_cvt_f32_i32 v30, v30
	v_cvt_f32_i32 v31, v31
	v_cvt_f32_i32 v32, v32
	v_cvt_f32_i32 v33, v33
	v_cvt_f32_i32 v10, v10
	v_cvt_f32_i32 v11, v11
	v_cvt_f32_i32 v12, v12
	v_cvt_f32_i32 v13, v13
	v_cvt_f32_i32 v22, v22
	v_cvt_f32_i32 v23, v23
	v_cvt_f32_i32 v24, v24
	v_cvt_f32_i32 v25, v25
	v_cvt_f32_i32 v6, v6
	v_cvt_f32_i32 v7, v7
	v_cvt_f32_i32 v8, v8
	v_cvt_f32_i32 v9, v9
	v_cvt_f32_i32 v18, v18
	v_cvt_f32_i32 v19, v19
	v_cvt_f32_i32 v20, v20
	v_cvt_f32_i32 v21, v21
	v_cvt_f32_i32 v2, v2
	v_cvt_f32_i32 v3, v3
	v_cvt_f32_i32 v4, v4
	v_cvt_f32_i32 v5, v5
	s_waitcnt vmcnt(0)
	v_pk_mul_f32 v[196:197], v[178:179], v[152:153] op_sel_hi:[1,0]
	v_pk_mul_f32 v[198:199], v[180:181], v[152:153] op_sel_hi:[1,0]
	v_pk_mul_f32 v[126:127], v[126:127], v[196:197]
	v_pk_mul_f32 v[196:197], v[178:179], v[154:155] op_sel_hi:[1,0]
	v_pk_mul_f32 v[128:129], v[128:129], v[198:199]
	v_pk_mul_f32 v[198:199], v[180:181], v[154:155] op_sel_hi:[1,0]
	v_pk_mul_f32 v[122:123], v[122:123], v[196:197]
	v_pk_mul_f32 v[196:197], v[178:179], v[156:157] op_sel_hi:[1,0]
	v_pk_mul_f32 v[124:125], v[124:125], v[198:199]
	v_pk_mul_f32 v[198:199], v[180:181], v[156:157] op_sel_hi:[1,0]
	v_pk_mul_f32 v[118:119], v[118:119], v[196:197]
	v_pk_mul_f32 v[196:197], v[178:179], v[158:159] op_sel_hi:[1,0]
	v_pk_mul_f32 v[120:121], v[120:121], v[198:199]
	v_pk_mul_f32 v[198:199], v[180:181], v[158:159] op_sel_hi:[1,0]
	v_pk_mul_f32 v[110:111], v[110:111], v[196:197]
	v_pk_mul_f32 v[196:197], v[178:179], v[194:195] op_sel_hi:[1,0]
	v_pk_mul_f32 v[112:113], v[112:113], v[198:199]
	v_pk_mul_f32 v[198:199], v[180:181], v[194:195] op_sel_hi:[1,0]
	v_pk_mul_f32 v[94:95], v[94:95], v[196:197]
	v_pk_mul_f32 v[196:197], v[178:179], v[160:161] op_sel_hi:[1,0]
	v_pk_mul_f32 v[96:97], v[96:97], v[198:199]
	v_pk_mul_f32 v[198:199], v[180:181], v[160:161] op_sel_hi:[1,0]
	v_pk_mul_f32 v[90:91], v[90:91], v[196:197]
	v_pk_mul_f32 v[196:197], v[178:179], v[162:163] op_sel_hi:[1,0]
	v_pk_mul_f32 v[178:179], v[178:179], v[164:165] op_sel_hi:[1,0]
	v_pk_mul_f32 v[92:93], v[92:93], v[198:199]
	v_pk_mul_f32 v[198:199], v[180:181], v[162:163] op_sel_hi:[1,0]
	v_pk_mul_f32 v[180:181], v[180:181], v[164:165] op_sel_hi:[1,0]
	v_pk_mul_f32 v[74:75], v[74:75], v[178:179]
	v_pk_mul_f32 v[178:179], v[152:153], v[182:183] op_sel_hi:[0,1]
	v_pk_mul_f32 v[76:77], v[76:77], v[180:181]
	v_pk_mul_f32 v[180:181], v[152:153], v[184:185] op_sel_hi:[0,1]
	v_pk_mul_f32 v[114:115], v[114:115], v[178:179]
	v_pk_mul_f32 v[178:179], v[154:155], v[182:183] op_sel_hi:[0,1]
	v_pk_mul_f32 v[116:117], v[116:117], v[180:181]
	v_pk_mul_f32 v[180:181], v[154:155], v[184:185] op_sel_hi:[0,1]
	v_pk_mul_f32 v[106:107], v[106:107], v[178:179]
	v_pk_mul_f32 v[178:179], v[156:157], v[182:183] op_sel_hi:[0,1]
	v_pk_mul_f32 v[108:109], v[108:109], v[180:181]
	v_pk_mul_f32 v[180:181], v[156:157], v[184:185] op_sel_hi:[0,1]
	v_pk_mul_f32 v[102:103], v[102:103], v[178:179]
	v_pk_mul_f32 v[178:179], v[158:159], v[182:183] op_sel_hi:[0,1]
	v_pk_mul_f32 v[104:105], v[104:105], v[180:181]
	v_pk_mul_f32 v[180:181], v[158:159], v[184:185] op_sel_hi:[0,1]
	v_pk_mul_f32 v[98:99], v[98:99], v[178:179]
	v_pk_mul_f32 v[178:179], v[194:195], v[182:183] op_sel_hi:[0,1]
	v_pk_mul_f32 v[100:101], v[100:101], v[180:181]
	v_pk_mul_f32 v[180:181], v[194:195], v[184:185] op_sel_hi:[0,1]
	v_pk_mul_f32 v[78:79], v[78:79], v[178:179]
	v_pk_mul_f32 v[178:179], v[160:161], v[182:183] op_sel_hi:[0,1]
	v_pk_mul_f32 v[80:81], v[80:81], v[180:181]
	v_pk_mul_f32 v[180:181], v[160:161], v[184:185] op_sel_hi:[0,1]
	v_pk_mul_f32 v[66:67], v[66:67], v[178:179]
	v_pk_mul_f32 v[178:179], v[182:183], v[162:163] op_sel_hi:[1,0]
	v_pk_mul_f32 v[68:69], v[68:69], v[180:181]
	v_pk_mul_f32 v[180:181], v[184:185], v[162:163] op_sel_hi:[1,0]
	v_pk_mul_f32 v[58:59], v[58:59], v[178:179]
	v_pk_mul_f32 v[178:179], v[182:183], v[164:165] op_sel_hi:[1,0]
	v_pk_mul_f32 v[60:61], v[60:61], v[180:181]
	v_pk_mul_f32 v[180:181], v[184:185], v[164:165] op_sel_hi:[1,0]
	v_pk_mul_f32 v[50:51], v[50:51], v[178:179]
	v_pk_mul_f32 v[178:179], v[152:153], v[186:187] op_sel_hi:[0,1]
	v_pk_mul_f32 v[52:53], v[52:53], v[180:181]
	v_pk_mul_f32 v[180:181], v[152:153], v[188:189] op_sel_hi:[0,1]
	v_pk_mul_f32 v[86:87], v[86:87], v[178:179]
	v_pk_mul_f32 v[178:179], v[154:155], v[186:187] op_sel_hi:[0,1]
	v_pk_mul_f32 v[88:89], v[88:89], v[180:181]
	v_pk_mul_f32 v[180:181], v[154:155], v[188:189] op_sel_hi:[0,1]
	v_pk_mul_f32 v[70:71], v[70:71], v[178:179]
	v_pk_mul_f32 v[178:179], v[156:157], v[186:187] op_sel_hi:[0,1]
	v_pk_mul_f32 v[72:73], v[72:73], v[180:181]
	v_pk_mul_f32 v[180:181], v[156:157], v[188:189] op_sel_hi:[0,1]
	v_pk_mul_f32 v[62:63], v[62:63], v[178:179]
	v_pk_mul_f32 v[178:179], v[158:159], v[186:187] op_sel_hi:[0,1]
	v_pk_mul_f32 v[64:65], v[64:65], v[180:181]
	v_pk_mul_f32 v[180:181], v[158:159], v[188:189] op_sel_hi:[0,1]
	v_pk_mul_f32 v[54:55], v[54:55], v[178:179]
	v_pk_mul_f32 v[178:179], v[194:195], v[186:187] op_sel_hi:[0,1]
	v_pk_mul_f32 v[56:57], v[56:57], v[180:181]
	v_pk_mul_f32 v[180:181], v[194:195], v[188:189] op_sel_hi:[0,1]
	v_pk_mul_f32 v[38:39], v[38:39], v[178:179]
	v_pk_mul_f32 v[178:179], v[160:161], v[186:187] op_sel_hi:[0,1]
	v_pk_mul_f32 v[40:41], v[40:41], v[180:181]
	v_pk_mul_f32 v[180:181], v[160:161], v[188:189] op_sel_hi:[0,1]
	v_pk_mul_f32 v[30:31], v[30:31], v[178:179]
	v_pk_mul_f32 v[178:179], v[162:163], v[186:187] op_sel_hi:[0,1]
	v_pk_mul_f32 v[32:33], v[32:33], v[180:181]
	v_pk_mul_f32 v[180:181], v[162:163], v[188:189] op_sel_hi:[0,1]
	v_pk_mul_f32 v[22:23], v[22:23], v[178:179]
	v_pk_mul_f32 v[178:179], v[186:187], v[164:165] op_sel_hi:[1,0]
	v_pk_mul_f32 v[24:25], v[24:25], v[180:181]
	v_pk_mul_f32 v[180:181], v[188:189], v[164:165] op_sel_hi:[1,0]
	v_pk_mul_f32 v[18:19], v[18:19], v[178:179]
	v_pk_mul_f32 v[178:179], v[152:153], v[190:191] op_sel_hi:[0,1]
	v_pk_mul_f32 v[20:21], v[20:21], v[180:181]
	v_pk_mul_f32 v[180:181], v[152:153], v[192:193] op_sel_hi:[0,1]
	v_pk_mul_f32 v[46:47], v[46:47], v[178:179]
	v_pk_mul_f32 v[178:179], v[154:155], v[190:191] op_sel_hi:[0,1]
	v_pk_mul_f32 v[48:49], v[48:49], v[180:181]
	v_pk_mul_f32 v[180:181], v[154:155], v[192:193] op_sel_hi:[0,1]
	v_pk_mul_f32 v[42:43], v[42:43], v[178:179]
	v_pk_mul_f32 v[178:179], v[156:157], v[190:191] op_sel_hi:[0,1]
	v_pk_mul_f32 v[44:45], v[44:45], v[180:181]
	v_pk_mul_f32 v[180:181], v[156:157], v[192:193] op_sel_hi:[0,1]
	v_pk_mul_f32 v[34:35], v[34:35], v[178:179]
	v_pk_mul_f32 v[178:179], v[158:159], v[190:191] op_sel_hi:[0,1]
	v_pk_mul_f32 v[36:37], v[36:37], v[180:181]
	v_pk_mul_f32 v[180:181], v[158:159], v[192:193] op_sel_hi:[0,1]
	v_pk_mul_f32 v[26:27], v[26:27], v[178:179]
	v_pk_mul_f32 v[178:179], v[194:195], v[190:191] op_sel_hi:[0,1]
	v_pk_mul_f32 v[28:29], v[28:29], v[180:181]
	v_pk_mul_f32 v[180:181], v[194:195], v[192:193] op_sel_hi:[0,1]
	v_pk_mul_f32 v[178:179], v[14:15], v[178:179]
	v_pk_mul_f32 v[14:15], v[160:161], v[190:191] op_sel_hi:[0,1]
	v_pk_mul_f32 v[180:181], v[16:17], v[180:181]
	v_pk_mul_f32 v[16:17], v[160:161], v[192:193] op_sel_hi:[0,1]
	v_pk_mul_f32 v[184:185], v[10:11], v[14:15]
	v_pk_mul_f32 v[10:11], v[162:163], v[190:191] op_sel_hi:[0,1]
	v_pk_mul_f32 v[182:183], v[12:13], v[16:17]
	v_pk_mul_f32 v[12:13], v[162:163], v[192:193] op_sel_hi:[0,1]
	v_pk_mul_f32 v[10:11], v[6:7], v[10:11]
	v_pk_mul_f32 v[6:7], v[164:165], v[190:191] op_sel_hi:[0,1]
	v_pk_mul_f32 v[8:9], v[8:9], v[12:13]
	v_pk_mul_f32 v[12:13], v[164:165], v[192:193] op_sel_hi:[0,1]
	v_pk_mul_f32 v[2:3], v[2:3], v[6:7]
	v_mov_b64_e32 v[6:7], s[10:11]
	v_pk_mul_f32 v[4:5], v[4:5], v[12:13]
	v_mad_i64_i32 v[14:15], s[26:27], v146, s47, v[6:7]
	v_lshlrev_b64 v[12:13], 1, v[150:151]
	v_lshl_add_u64 v[150:151], v[14:15], 0, v[12:13]
	v_cvt_pk_bf16_f32 v14, v126, v127
	v_cvt_pk_bf16_f32 v15, v128, v129
	v_cvt_pk_bf16_f32 v16, v114, v115
	v_cvt_pk_bf16_f32 v17, v116, v117
	global_store_dwordx4 v[150:151], v[14:17], off
	v_pk_mul_f32 v[84:85], v[84:85], v[198:199]
	v_pk_mul_f32 v[82:83], v[82:83], v[196:197]
	v_cvt_pk_bf16_f32 v14, v86, v87
	v_cvt_pk_bf16_f32 v15, v88, v89
	v_cvt_pk_bf16_f32 v16, v46, v47
	v_cvt_pk_bf16_f32 v17, v48, v49
	global_store_dwordx4 v[150:151], v[14:17], off offset:256
	s_nop 1
	v_or_b32_e32 v14, 16, v146
	v_mad_i64_i32 v[14:15], s[26:27], v14, s47, v[6:7]
	v_lshl_add_u64 v[46:47], v[14:15], 0, v[12:13]
	v_cvt_pk_bf16_f32 v14, v122, v123
	v_cvt_pk_bf16_f32 v15, v124, v125
	v_cvt_pk_bf16_f32 v16, v106, v107
	v_cvt_pk_bf16_f32 v17, v108, v109
	global_store_dwordx4 v[46:47], v[14:17], off
	s_nop 1
	v_cvt_pk_bf16_f32 v14, v70, v71
	v_cvt_pk_bf16_f32 v15, v72, v73
	v_cvt_pk_bf16_f32 v16, v42, v43
	v_cvt_pk_bf16_f32 v17, v44, v45
	global_store_dwordx4 v[46:47], v[14:17], off offset:256
	s_nop 1
	v_or_b32_e32 v14, 32, v146
	v_mad_i64_i32 v[14:15], s[26:27], v14, s47, v[6:7]
	v_lshl_add_u64 v[42:43], v[14:15], 0, v[12:13]
	v_cvt_pk_bf16_f32 v14, v118, v119
	v_cvt_pk_bf16_f32 v15, v120, v121
	v_cvt_pk_bf16_f32 v16, v102, v103
	v_cvt_pk_bf16_f32 v17, v104, v105
	global_store_dwordx4 v[42:43], v[14:17], off
	s_nop 1
	v_cvt_pk_bf16_f32 v14, v62, v63
	v_cvt_pk_bf16_f32 v15, v64, v65
	v_cvt_pk_bf16_f32 v16, v34, v35
	v_cvt_pk_bf16_f32 v17, v36, v37
	global_store_dwordx4 v[42:43], v[14:17], off offset:256
	s_nop 1
	v_or_b32_e32 v14, 48, v146
	v_mad_i64_i32 v[14:15], s[26:27], v14, s47, v[6:7]
	v_lshl_add_u64 v[34:35], v[14:15], 0, v[12:13]
	v_cvt_pk_bf16_f32 v14, v110, v111
	v_cvt_pk_bf16_f32 v15, v112, v113
	v_cvt_pk_bf16_f32 v16, v98, v99
	v_cvt_pk_bf16_f32 v17, v100, v101
	global_store_dwordx4 v[34:35], v[14:17], off
	s_nop 1
	v_cvt_pk_bf16_f32 v14, v54, v55
	v_cvt_pk_bf16_f32 v15, v56, v57
	v_cvt_pk_bf16_f32 v16, v26, v27
	v_cvt_pk_bf16_f32 v17, v28, v29
	global_store_dwordx4 v[34:35], v[14:17], off offset:256
	s_nop 1
	v_mad_i64_i32 v[14:15], s[26:27], v148, s47, v[6:7]
	v_lshl_add_u64 v[26:27], v[14:15], 0, v[12:13]
	v_cvt_pk_bf16_f32 v14, v94, v95
	v_cvt_pk_bf16_f32 v15, v96, v97
	v_cvt_pk_bf16_f32 v16, v78, v79
	v_cvt_pk_bf16_f32 v17, v80, v81
	global_store_dwordx4 v[26:27], v[14:17], off
	s_nop 1
	v_cvt_pk_bf16_f32 v14, v38, v39
	v_cvt_pk_bf16_f32 v15, v40, v41
	v_cvt_pk_bf16_f32 v16, v178, v179
	v_cvt_pk_bf16_f32 v17, v180, v181
	global_store_dwordx4 v[26:27], v[14:17], off offset:256
	s_nop 1
	v_add_u32_e32 v14, 0x90, v146
	v_mad_i64_i32 v[14:15], s[26:27], v14, s47, v[6:7]
	v_lshl_add_u64 v[26:27], v[14:15], 0, v[12:13]
	v_cvt_pk_bf16_f32 v14, v90, v91
	v_cvt_pk_bf16_f32 v15, v92, v93
	v_cvt_pk_bf16_f32 v16, v66, v67
	v_cvt_pk_bf16_f32 v17, v68, v69
	global_store_dwordx4 v[26:27], v[14:17], off
	s_nop 1
	v_cvt_pk_bf16_f32 v14, v30, v31
	v_cvt_pk_bf16_f32 v15, v32, v33
	v_cvt_pk_bf16_f32 v16, v184, v185
	v_cvt_pk_bf16_f32 v17, v182, v183
	global_store_dwordx4 v[26:27], v[14:17], off offset:256
	s_nop 1
	v_add_u32_e32 v14, 0xa0, v146
	v_mad_i64_i32 v[14:15], s[26:27], v14, s47, v[6:7]
	v_lshl_add_u64 v[26:27], v[14:15], 0, v[12:13]
	v_cvt_pk_bf16_f32 v14, v82, v83
	v_cvt_pk_bf16_f32 v15, v84, v85
	v_cvt_pk_bf16_f32 v16, v58, v59
	v_cvt_pk_bf16_f32 v17, v60, v61
	global_store_dwordx4 v[26:27], v[14:17], off
	s_nop 1
	v_cvt_pk_bf16_f32 v14, v22, v23
	v_cvt_pk_bf16_f32 v15, v24, v25
	v_cvt_pk_bf16_f32 v16, v10, v11
	v_cvt_pk_bf16_f32 v17, v8, v9
	v_add_u32_e32 v8, 0xb0, v146
	v_mad_i64_i32 v[6:7], s[26:27], v8, s47, v[6:7]
	global_store_dwordx4 v[26:27], v[14:17], off offset:256
	v_lshl_add_u64 v[10:11], v[6:7], 0, v[12:13]
	v_cvt_pk_bf16_f32 v6, v74, v75
	v_cvt_pk_bf16_f32 v7, v76, v77
	v_cvt_pk_bf16_f32 v8, v50, v51
	v_cvt_pk_bf16_f32 v9, v52, v53
	global_store_dwordx4 v[10:11], v[6:9], off
	s_nop 1
	v_cvt_pk_bf16_f32 v6, v18, v19
	v_cvt_pk_bf16_f32 v7, v20, v21
	v_cvt_pk_bf16_f32 v8, v2, v3
	v_cvt_pk_bf16_f32 v9, v4, v5
	global_store_dwordx4 v[10:11], v[6:9], off offset:256
	s_cbranch_vccnz .LBB0_192
	s_andn2_b64 vcc, exec, s[0:1]
	s_cbranch_vccnz .LBB0_191
	s_barrier
	s_branch .LBB0_191

.LBB0_464:
	s_min_i32 s5, s84, 0x80
	v_readlane_b32 s0, v254, 0
	s_waitcnt vmcnt(0)
	v_lshrrev_b32_e32 v2, 6, v0
	s_mov_b32 s2, s0
	s_cmp_ge_i32 s0, s5
	s_mul_i32 s0, s0, 2
	v_add3_u32 v3, v2, s0, -1
	s_cselect_b64 vcc, -1, 0
	s_sub_i32 s0, s2, s5
	s_mul_i32 s4, s5, 2
	s_lshl_b32 s0, s0, 3
	s_add_i32 s0, s0, s4
	v_readlane_b32 s1, v254, 1
	v_add_u32_e32 v2, s0, v2
	v_add_u32_e32 v31, -64, v0
	s_movk_i32 s7, 0x80
	v_cmp_gt_u32_e64 s[0:1], s7, v31
	v_cndmask_b32_e32 v30, v3, v2, vcc
	s_mov_b32 s6, 0x18200
	s_or_b64 s[0:1], vcc, s[0:1]
	v_cmp_gt_i32_e32 vcc, s6, v30
	s_movk_i32 s3, 0x80
	s_and_b64 s[6:7], s[0:1], vcc
	s_and_saveexec_b64 s[0:1], s[6:7]
	s_cbranch_execz .LBB0_491
	s_sub_i32 s5, s84, s5
	v_lshlrev_b32_e32 v2, 8, v0
	s_lshl_b32 s33, s5, 3
	v_and_b32_e32 v2, 0x1c000, v2
	s_add_i32 s33, s33, s4
	v_add_u32_e32 v7, 0, v2
	v_lshlrev_b32_e32 v2, 4, v0
	v_and_b32_e32 v24, 0x70, v2
	v_lshlrev_b32_e32 v2, 3, v0
	s_add_u32 s6, s66, 0x8100000
	v_and_b32_e32 v2, 56, v2
	s_addc_u32 s7, s67, 0
	v_mul_u32_u24_e32 v6, 0x84, v2
	v_lshlrev_b32_e32 v2, 1, v2
	v_mov_b32_e32 v3, 0
	s_add_u32 s8, s66, 0x93400
	v_lshl_add_u64 v[12:13], s[66:67], 0, v[2:3]
	s_addc_u32 s9, s67, 0
	s_mov_b64 s[12:13], 0x6100000
	s_add_u32 s10, s66, 0xbc000
	v_lshl_add_u64 v[8:9], v[12:13], 0, s[12:13]
	s_mov_b64 s[12:13], 0x5100000
	s_mov_b64 s[4:5], 0x12d00000
	s_addc_u32 s11, s67, 0
	v_lshl_add_u64 v[10:11], v[12:13], 0, s[12:13]
	s_mov_b64 s[12:13], 0x4100000
	v_lshl_add_u64 v[4:5], v[12:13], 0, s[4:5]
	v_lshl_add_u64 v[12:13], v[12:13], 0, s[12:13]
	s_add_u32 s12, s66, 0x100000
	s_addc_u32 s13, s67, 0
	v_readlane_b32 s36, v254, 20
	v_lshrrev_b32_e32 v31, 3, v1
	s_add_u32 s14, s66, 0x8b400
	v_readlane_b32 s40, v254, 24
	v_readlane_b32 s41, v254, 25
	v_add_u32_e32 v26, v7, v24
	v_mul_u32_u24_e32 v27, 0x84, v31
	s_addc_u32 s15, s67, 0
	v_readlane_b32 s42, v254, 26
	v_readlane_b32 s43, v254, 27
	v_readlane_b32 s44, v254, 28
	v_readlane_b32 s45, v254, 29
	v_readlane_b32 s46, v254, 30
	v_readlane_b32 s47, v254, 31
	v_readlane_b32 s48, v254, 32
	v_readlane_b32 s49, v254, 33
	v_readlane_b32 s50, v254, 34
	v_readlane_b32 s51, v254, 35
	s_mov_b64 s[20:21], s[40:41]
	v_lshlrev_b32_e32 v2, 2, v31
	v_lshrrev_b32_e32 v1, 1, v1
	v_and_b32_e32 v40, 1, v0
	s_add_u32 s16, s66, 0xb4000
	v_mov_b32_e32 v25, v3
	v_readlane_b32 s37, v254, 21
	v_readlane_b32 s38, v254, 22
	v_readlane_b32 s39, v254, 23
	s_mov_b64 s[24:25], s[44:45]
	s_mov_b64 s[26:27], s[46:47]
	s_mov_b64 s[28:29], s[48:49]
	s_mov_b64 s[30:31], s[50:51]
	v_add_u32_e32 v44, v26, v27
	v_or_b32_e32 v32, 8, v31
	v_or_b32_e32 v33, 16, v31
	v_or_b32_e32 v34, 24, v31
	v_or_b32_e32 v35, 32, v31
	v_or_b32_e32 v36, 40, v31
	v_or_b32_e32 v37, 48, v31
	v_or_b32_e32 v38, 56, v31
	v_add3_u32 v39, v7, v6, v2
	v_lshlrev_b32_e32 v6, 5, v40
	v_lshl_add_u32 v41, v1, 2, v7
	v_mul_u32_u24_e32 v42, 0x1080, v40
	v_mov_b32_e32 v7, v3
	v_cmp_eq_u32_e64 s[4:5], 0, v40
	s_addc_u32 s17, s67, 0
	v_lshl_add_u64 v[14:15], s[60:61], 0, v[24:25]
	v_lshl_add_u64 v[16:17], s[54:55], 0, v[24:25]
	s_mov_b64 s[22:23], s[42:43]
	v_lshl_add_u64 v[18:19], s[30:31], 0, v[24:25]
	v_lshl_add_u64 v[20:21], s[26:27], 0, v[24:25]
	v_lshl_add_u64 v[22:23], s[24:25], 0, v[24:25]
	v_lshl_add_u64 v[24:25], s[28:29], 0, v[24:25]
	v_lshlrev_b32_e32 v43, 5, v30
	s_lshl_b32 s34, s33, 5
	s_mov_b64 s[18:19], 0
	s_movk_i32 s35, 0x3fff
	s_movk_i32 s36, 0x4fff
	s_movk_i32 s37, 0x5fff
	s_movk_i32 s38, 0x7fff
	s_mov_b32 s39, 0x12bff
	v_add_u32_e32 v45, 0x420, v44
	v_add_u32_e32 v46, 0x428, v44
	v_add_u32_e32 v47, 0x840, v44
	v_add_u32_e32 v48, 0x848, v44
	v_add_u32_e32 v49, 0xc60, v44
	v_add_u32_e32 v50, 0xc68, v44
	s_mov_b32 s40, 0xffff0000
	s_mov_b32 s41, 0xbe83
	s_movk_i32 s42, 0x2b0
	s_movk_i32 s43, 0x2a80
	s_mov_b32 s44, 0x42fe0000
	s_mov_b32 s45, 0xc0c0500
	s_mov_b32 s46, 0x181ff
	v_add_u32_e32 v51, 0x1080, v44
	v_add_u32_e32 v52, 0x1088, v44
	v_add_u32_e32 v53, 0x14a0, v44
	v_add_u32_e32 v54, 0x14a8, v44
	v_add_u32_e32 v55, 0x18c0, v44
	s_branch .LBB0_468

.LBB0_703:
	s_mov_b32 s94, 0x7fff0000
	s_mov_b32 s95, 0x7fff0000
	s_mov_b32 s97, 0
	v_lshlrev_b32_e32 v238, 2, v121
	v_readfirstlane_b32 s16, v0
	s_nop 3
	s_lshr_b32 s16, s16, 6
	s_cmp_ge_u32 s16, 4
	s_cbranch_scc0 .Ltk_noprio
	s_setprio 1
.Ltk_noprio:
.Ltk_block:
	s_add_i32 s30, s30, 1
	s_cmp_lt_u32 s30, s24
	s_cbranch_scc0 .Ltk_nopf
	v_lshl_or_b32 v242, s30, 8, v102
	v_mov_b32_e32 v243, s21
	v_cmp_gt_i32_e32 vcc, s22, v242
	s_nop 1
	v_cndmask_b32_e32 v242, v243, v242, vcc
	v_ashrrev_i32_e32 v243, 31, v242
	v_lshlrev_b64 v[242:243], 7, v[242:243]
	v_lshl_add_u64 v[242:243], v[84:85], 0, v[242:243]
	global_load_dwordx4 v[46:49], v[242:243], off offset:48
	global_load_dwordx4 v[42:45], v[242:243], off offset:32
	global_load_dwordx4 v[38:41], v[242:243], off offset:16
	global_load_dwordx4 v[34:37], v[242:243], off

.Ltk_done:
	s_setprio 0
	s_waitcnt lgkmcnt(0)
	s_barrier
	s_branch .LBB0_717

.LBB0_1485:
	v_lshl_or_b32 v150, s33, 8, v155
	v_ashrrev_i32_e32 v151, 31, v150
	v_lshl_add_u32 v148, s30, 8, v1
	v_lshl_add_u64 v[178:179], v[150:151], 2, s[8:9]
	global_load_dwordx4 v[166:169], v[178:179], off
	v_ashrrev_i32_e32 v149, 31, v148
	v_lshl_add_u64 v[164:165], v[148:149], 2, s[6:7]
	global_load_dword v152, v[164:165], off
	global_load_dword v154, v[164:165], off offset:64
	global_load_dword v156, v[164:165], off offset:128
	v_add_u32_e32 v146, 0x80, v148
	v_ashrrev_i32_e32 v147, 31, v146
	v_lshl_add_u64 v[170:171], v[146:147], 2, s[6:7]
	global_load_dword v158, v[164:165], off offset:192
	global_load_dword v160, v[164:165], off offset:576
	global_load_dword v162, v[164:165], off offset:640
	s_nop 0
	global_load_dword v164, v[164:165], off offset:704
	s_nop 0
	global_load_dword v182, v[170:171], off
	s_nop 0
	global_load_dwordx4 v[170:173], v[178:179], off offset:16
	global_load_dwordx4 v[174:177], v[178:179], off offset:512
	s_nop 0
	global_load_dwordx4 v[178:181], v[178:179], off offset:528
	s_nop 15
	s_nop 15
	v_cvt_f32_i32 v126, v126
	v_cvt_f32_i32 v127, v127
	v_cvt_f32_i32 v128, v128
	v_cvt_f32_i32 v129, v129
	v_cvt_f32_i32 v114, v114
	v_cvt_f32_i32 v115, v115
	v_cvt_f32_i32 v116, v116
	v_cvt_f32_i32 v117, v117
	v_cvt_f32_i32 v122, v122
	v_cvt_f32_i32 v123, v123
	v_cvt_f32_i32 v124, v124
	v_cvt_f32_i32 v125, v125
	v_cvt_f32_i32 v106, v106
	v_cvt_f32_i32 v107, v107
	v_cvt_f32_i32 v108, v108
	v_cvt_f32_i32 v109, v109
	v_cvt_f32_i32 v118, v118
	v_cvt_f32_i32 v119, v119
	v_cvt_f32_i32 v120, v120
	v_cvt_f32_i32 v121, v121
	v_cvt_f32_i32 v102, v102
	v_cvt_f32_i32 v103, v103
	v_cvt_f32_i32 v104, v104
	v_cvt_f32_i32 v105, v105
	v_cvt_f32_i32 v110, v110
	v_cvt_f32_i32 v111, v111
	v_cvt_f32_i32 v112, v112
	v_cvt_f32_i32 v113, v113
	v_cvt_f32_i32 v98, v98
	v_cvt_f32_i32 v99, v99
	v_cvt_f32_i32 v100, v100
	v_cvt_f32_i32 v101, v101
	v_cvt_f32_i32 v86, v86
	v_cvt_f32_i32 v87, v87
	v_cvt_f32_i32 v88, v88
	v_cvt_f32_i32 v89, v89
	v_cvt_f32_i32 v46, v46
	v_cvt_f32_i32 v47, v47
	v_cvt_f32_i32 v48, v48
	v_cvt_f32_i32 v49, v49
	v_cvt_f32_i32 v70, v70
	v_cvt_f32_i32 v71, v71
	v_cvt_f32_i32 v72, v72
	v_cvt_f32_i32 v73, v73
	v_cvt_f32_i32 v42, v42
	v_cvt_f32_i32 v43, v43
	v_cvt_f32_i32 v44, v44
	v_cvt_f32_i32 v45, v45
	v_cvt_f32_i32 v62, v62
	v_cvt_f32_i32 v63, v63
	v_cvt_f32_i32 v64, v64
	v_cvt_f32_i32 v65, v65
	v_cvt_f32_i32 v34, v34
	v_cvt_f32_i32 v35, v35
	v_cvt_f32_i32 v36, v36
	v_cvt_f32_i32 v37, v37
	v_cvt_f32_i32 v54, v54
	v_cvt_f32_i32 v55, v55
	v_cvt_f32_i32 v56, v56
	v_cvt_f32_i32 v57, v57
	v_cvt_f32_i32 v26, v26
	v_cvt_f32_i32 v27, v27
	v_cvt_f32_i32 v28, v28
	v_cvt_f32_i32 v29, v29
	v_cvt_f32_i32 v94, v94
	v_cvt_f32_i32 v95, v95
	v_cvt_f32_i32 v96, v96
	v_cvt_f32_i32 v97, v97
	v_cvt_f32_i32 v78, v78
	v_cvt_f32_i32 v79, v79
	v_cvt_f32_i32 v80, v80
	v_cvt_f32_i32 v81, v81
	v_cvt_f32_i32 v90, v90
	v_cvt_f32_i32 v91, v91
	v_cvt_f32_i32 v92, v92
	v_cvt_f32_i32 v93, v93
	v_cvt_f32_i32 v66, v66
	v_cvt_f32_i32 v67, v67
	v_cvt_f32_i32 v68, v68
	v_cvt_f32_i32 v69, v69
	v_cvt_f32_i32 v82, v82
	v_cvt_f32_i32 v83, v83
	v_cvt_f32_i32 v84, v84
	v_cvt_f32_i32 v85, v85
	v_cvt_f32_i32 v58, v58
	v_cvt_f32_i32 v59, v59
	v_cvt_f32_i32 v60, v60
	v_cvt_f32_i32 v61, v61
	v_cvt_f32_i32 v74, v74
	v_cvt_f32_i32 v75, v75
	v_cvt_f32_i32 v76, v76
	v_cvt_f32_i32 v77, v77
	v_cvt_f32_i32 v50, v50
	v_cvt_f32_i32 v51, v51
	v_cvt_f32_i32 v52, v52
	v_cvt_f32_i32 v53, v53
	v_cvt_f32_i32 v38, v38
	v_cvt_f32_i32 v39, v39
	v_cvt_f32_i32 v40, v40
	v_cvt_f32_i32 v41, v41
	v_cvt_f32_i32 v14, v14
	v_cvt_f32_i32 v15, v15
	v_cvt_f32_i32 v16, v16
	v_cvt_f32_i32 v17, v17
	v_cvt_f32_i32 v30, v30
	v_cvt_f32_i32 v31, v31
	v_cvt_f32_i32 v32, v32
	v_cvt_f32_i32 v33, v33
	v_cvt_f32_i32 v10, v10
	v_cvt_f32_i32 v11, v11
	v_cvt_f32_i32 v12, v12
	v_cvt_f32_i32 v13, v13
	v_cvt_f32_i32 v22, v22
	v_cvt_f32_i32 v23, v23
	v_cvt_f32_i32 v24, v24
	v_cvt_f32_i32 v25, v25
	v_cvt_f32_i32 v6, v6
	v_cvt_f32_i32 v7, v7
	v_cvt_f32_i32 v8, v8
	v_cvt_f32_i32 v9, v9
	v_cvt_f32_i32 v18, v18
	v_cvt_f32_i32 v19, v19
	v_cvt_f32_i32 v20, v20
	v_cvt_f32_i32 v21, v21
	v_cvt_f32_i32 v2, v2
	v_cvt_f32_i32 v3, v3
	v_cvt_f32_i32 v4, v4
	v_cvt_f32_i32 v5, v5
	s_waitcnt vmcnt(0)
	v_pk_mul_f32 v[184:185], v[166:167], v[152:153] op_sel_hi:[1,0]
	s_nop 0
	v_pk_mul_f32 v[184:185], v[126:127], v[184:185]
	v_pk_mul_f32 v[126:127], v[166:167], v[154:155] op_sel_hi:[1,0]
	v_pk_mul_f32 v[186:187], v[168:169], v[152:153] op_sel_hi:[1,0]
	v_pk_mul_f32 v[122:123], v[122:123], v[126:127]
	v_pk_mul_f32 v[126:127], v[166:167], v[156:157] op_sel_hi:[1,0]
	v_pk_mul_f32 v[128:129], v[128:129], v[186:187]
	v_pk_mul_f32 v[118:119], v[118:119], v[126:127]
	v_pk_mul_f32 v[126:127], v[166:167], v[158:159] op_sel_hi:[1,0]
	v_pk_mul_f32 v[186:187], v[168:169], v[154:155] op_sel_hi:[1,0]
	v_pk_mul_f32 v[110:111], v[110:111], v[126:127]
	v_pk_mul_f32 v[126:127], v[166:167], v[182:183] op_sel_hi:[1,0]
	v_pk_mul_f32 v[124:125], v[124:125], v[186:187]
	v_pk_mul_f32 v[94:95], v[94:95], v[126:127]
	v_pk_mul_f32 v[126:127], v[166:167], v[160:161] op_sel_hi:[1,0]
	v_pk_mul_f32 v[186:187], v[168:169], v[156:157] op_sel_hi:[1,0]
	v_pk_mul_f32 v[90:91], v[90:91], v[126:127]
	v_pk_mul_f32 v[126:127], v[166:167], v[162:163] op_sel_hi:[1,0]
	v_pk_mul_f32 v[120:121], v[120:121], v[186:187]
	v_pk_mul_f32 v[82:83], v[82:83], v[126:127]
	v_pk_mul_f32 v[126:127], v[166:167], v[164:165] op_sel_hi:[1,0]
	v_pk_mul_f32 v[166:167], v[168:169], v[164:165] op_sel_hi:[1,0]
	v_pk_mul_f32 v[74:75], v[74:75], v[126:127]
	v_pk_mul_f32 v[76:77], v[76:77], v[166:167]
	v_pk_mul_f32 v[126:127], v[152:153], v[170:171] op_sel_hi:[0,1]
	v_pk_mul_f32 v[166:167], v[152:153], v[172:173] op_sel_hi:[0,1]
	v_pk_mul_f32 v[116:117], v[116:117], v[166:167]
	v_pk_mul_f32 v[166:167], v[114:115], v[126:127]
	v_pk_mul_f32 v[114:115], v[154:155], v[170:171] op_sel_hi:[0,1]
	v_pk_mul_f32 v[126:127], v[154:155], v[172:173] op_sel_hi:[0,1]
	v_pk_mul_f32 v[108:109], v[108:109], v[126:127]
	v_pk_mul_f32 v[106:107], v[106:107], v[114:115]
	v_pk_mul_f32 v[114:115], v[156:157], v[170:171] op_sel_hi:[0,1]
	v_pk_mul_f32 v[126:127], v[156:157], v[172:173] op_sel_hi:[0,1]
	v_pk_mul_f32 v[104:105], v[104:105], v[126:127]
	v_pk_mul_f32 v[102:103], v[102:103], v[114:115]
	v_pk_mul_f32 v[114:115], v[158:159], v[170:171] op_sel_hi:[0,1]
	v_pk_mul_f32 v[126:127], v[158:159], v[172:173] op_sel_hi:[0,1]
	v_pk_mul_f32 v[100:101], v[100:101], v[126:127]
	v_pk_mul_f32 v[98:99], v[98:99], v[114:115]
	v_pk_mul_f32 v[114:115], v[182:183], v[170:171] op_sel_hi:[0,1]
	v_pk_mul_f32 v[126:127], v[182:183], v[172:173] op_sel_hi:[0,1]
	v_pk_mul_f32 v[80:81], v[80:81], v[126:127]
	v_pk_mul_f32 v[78:79], v[78:79], v[114:115]
	v_pk_mul_f32 v[114:115], v[160:161], v[170:171] op_sel_hi:[0,1]
	v_pk_mul_f32 v[126:127], v[160:161], v[172:173] op_sel_hi:[0,1]
	v_pk_mul_f32 v[68:69], v[68:69], v[126:127]
	v_pk_mul_f32 v[66:67], v[66:67], v[114:115]
	v_pk_mul_f32 v[114:115], v[170:171], v[162:163] op_sel_hi:[1,0]
	v_pk_mul_f32 v[126:127], v[172:173], v[162:163] op_sel_hi:[1,0]
	v_pk_mul_f32 v[58:59], v[58:59], v[114:115]
	v_pk_mul_f32 v[60:61], v[60:61], v[126:127]
	v_pk_mul_f32 v[114:115], v[170:171], v[164:165] op_sel_hi:[1,0]
	v_pk_mul_f32 v[126:127], v[172:173], v[164:165] op_sel_hi:[1,0]
	v_pk_mul_f32 v[50:51], v[50:51], v[114:115]
	v_pk_mul_f32 v[52:53], v[52:53], v[126:127]
	v_pk_mul_f32 v[114:115], v[152:153], v[174:175] op_sel_hi:[0,1]
	v_pk_mul_f32 v[126:127], v[152:153], v[176:177] op_sel_hi:[0,1]
	v_pk_mul_f32 v[88:89], v[88:89], v[126:127]
	v_pk_mul_f32 v[114:115], v[86:87], v[114:115]
	v_pk_mul_f32 v[86:87], v[154:155], v[174:175] op_sel_hi:[0,1]
	v_pk_mul_f32 v[126:127], v[154:155], v[176:177] op_sel_hi:[0,1]
	v_pk_mul_f32 v[72:73], v[72:73], v[126:127]
	v_pk_mul_f32 v[70:71], v[70:71], v[86:87]
	v_pk_mul_f32 v[86:87], v[156:157], v[174:175] op_sel_hi:[0,1]
	v_pk_mul_f32 v[126:127], v[156:157], v[176:177] op_sel_hi:[0,1]
	v_pk_mul_f32 v[64:65], v[64:65], v[126:127]
	v_pk_mul_f32 v[62:63], v[62:63], v[86:87]
	v_pk_mul_f32 v[86:87], v[158:159], v[174:175] op_sel_hi:[0,1]
	v_pk_mul_f32 v[126:127], v[158:159], v[176:177] op_sel_hi:[0,1]
	v_pk_mul_f32 v[56:57], v[56:57], v[126:127]
	v_pk_mul_f32 v[54:55], v[54:55], v[86:87]
	v_pk_mul_f32 v[86:87], v[182:183], v[174:175] op_sel_hi:[0,1]
	v_pk_mul_f32 v[126:127], v[182:183], v[176:177] op_sel_hi:[0,1]
	v_pk_mul_f32 v[40:41], v[40:41], v[126:127]
	v_pk_mul_f32 v[38:39], v[38:39], v[86:87]
	v_pk_mul_f32 v[86:87], v[160:161], v[174:175] op_sel_hi:[0,1]
	v_pk_mul_f32 v[126:127], v[160:161], v[176:177] op_sel_hi:[0,1]
	v_pk_mul_f32 v[32:33], v[32:33], v[126:127]
	v_pk_mul_f32 v[30:31], v[30:31], v[86:87]
	v_pk_mul_f32 v[86:87], v[162:163], v[174:175] op_sel_hi:[0,1]
	v_pk_mul_f32 v[126:127], v[162:163], v[176:177] op_sel_hi:[0,1]
	v_pk_mul_f32 v[24:25], v[24:25], v[126:127]
	v_pk_mul_f32 v[22:23], v[22:23], v[86:87]
	v_pk_mul_f32 v[86:87], v[174:175], v[164:165] op_sel_hi:[1,0]
	v_pk_mul_f32 v[126:127], v[176:177], v[164:165] op_sel_hi:[1,0]
	v_pk_mul_f32 v[18:19], v[18:19], v[86:87]
	v_pk_mul_f32 v[20:21], v[20:21], v[126:127]
	v_pk_mul_f32 v[126:127], v[152:153], v[178:179] op_sel_hi:[0,1]
	v_pk_mul_f32 v[86:87], v[152:153], v[180:181] op_sel_hi:[0,1]
	v_pk_mul_f32 v[86:87], v[48:49], v[86:87]
	v_pk_mul_f32 v[126:127], v[46:47], v[126:127]
	v_pk_mul_f32 v[48:49], v[154:155], v[178:179] op_sel_hi:[0,1]
	v_pk_mul_f32 v[46:47], v[154:155], v[180:181] op_sel_hi:[0,1]
	v_pk_mul_f32 v[46:47], v[44:45], v[46:47]
	v_pk_mul_f32 v[48:49], v[42:43], v[48:49]
	v_pk_mul_f32 v[44:45], v[156:157], v[178:179] op_sel_hi:[0,1]
	v_pk_mul_f32 v[42:43], v[156:157], v[180:181] op_sel_hi:[0,1]
	v_pk_mul_f32 v[42:43], v[36:37], v[42:43]
	v_pk_mul_f32 v[44:45], v[34:35], v[44:45]
	v_pk_mul_f32 v[34:35], v[158:159], v[178:179] op_sel_hi:[0,1]
	v_pk_mul_f32 v[36:37], v[158:159], v[180:181] op_sel_hi:[0,1]
	v_mul_f32_e32 v152, 0xbfb8aa3b, v184
	v_pk_mul_f32 v[28:29], v[28:29], v[36:37]
	v_pk_mul_f32 v[36:37], v[26:27], v[34:35]
	v_pk_mul_f32 v[26:27], v[182:183], v[178:179] op_sel_hi:[0,1]
	v_exp_f32_e32 v152, v152
	v_pk_mul_f32 v[26:27], v[14:15], v[26:27]
	v_pk_mul_f32 v[14:15], v[160:161], v[178:179] op_sel_hi:[0,1]
	v_pk_mul_f32 v[14:15], v[10:11], v[14:15]
	v_pk_mul_f32 v[10:11], v[162:163], v[178:179] op_sel_hi:[0,1]
	v_pk_mul_f32 v[10:11], v[6:7], v[10:11]
	v_pk_mul_f32 v[6:7], v[164:165], v[178:179] op_sel_hi:[0,1]
	v_pk_mul_f32 v[2:3], v[2:3], v[6:7]
	v_lshlrev_b64 v[6:7], 14, v[148:149]
	v_add_f32_e32 v149, 1.0, v152
	v_pk_mul_f32 v[34:35], v[182:183], v[180:181] op_sel_hi:[0,1]
	v_pk_mul_f32 v[16:17], v[16:17], v[34:35]
	v_pk_mul_f32 v[34:35], v[160:161], v[180:181] op_sel_hi:[0,1]
	v_pk_mul_f32 v[12:13], v[12:13], v[34:35]
	v_pk_mul_f32 v[34:35], v[162:163], v[180:181] op_sel_hi:[0,1]
	v_pk_mul_f32 v[8:9], v[8:9], v[34:35]
	v_pk_mul_f32 v[34:35], v[164:165], v[180:181] op_sel_hi:[0,1]
	v_pk_mul_f32 v[4:5], v[4:5], v[34:35]
	v_lshlrev_b64 v[34:35], 1, v[150:151]
	v_mul_f32_e32 v156, 0xbfb8aa3b, v166
	v_exp_f32_e32 v156, v156
	v_pk_mul_f32 v[186:187], v[168:169], v[158:159] op_sel_hi:[1,0]
	v_add_f32_e32 v152, 1.0, v156
	v_mul_f32_e32 v154, 0xbfb8aa3b, v185
	v_rcp_f32_e32 v149, v149
	v_exp_f32_e32 v154, v154
	v_pk_mul_f32 v[112:113], v[112:113], v[186:187]
	v_pk_mul_f32 v[186:187], v[168:169], v[182:183] op_sel_hi:[1,0]
	v_pk_mul_f32 v[96:97], v[96:97], v[186:187]
	v_pk_mul_f32 v[186:187], v[168:169], v[160:161] op_sel_hi:[1,0]
	v_add_f32_e32 v154, 1.0, v154
	v_mul_f32_e32 v158, 0xbfb8aa3b, v167
	v_exp_f32_e32 v158, v158
	v_rcp_f32_e32 v150, v152
	v_pk_mul_f32 v[92:93], v[92:93], v[186:187]
	v_pk_mul_f32 v[186:187], v[168:169], v[162:163] op_sel_hi:[1,0]
	v_add_f32_e32 v156, 1.0, v158
	v_mul_f32_e32 v128, 0xbfb8aa3b, v128
	v_exp_f32_e32 v128, v128
	v_rcp_f32_e32 v151, v154
	v_add_f32_e32 v128, 1.0, v128
	v_mul_f32_e32 v116, 0xbfb8aa3b, v116
	v_exp_f32_e32 v116, v116
	v_rcp_f32_e32 v152, v156
	v_add_f32_e32 v116, 1.0, v116
	v_mul_f32_e32 v129, 0xbfb8aa3b, v129
	v_rcp_f32_e32 v128, v128
	v_exp_f32_e32 v129, v129
	s_nop 0
	v_add_f32_e32 v129, 1.0, v129
	v_mul_f32_e32 v117, 0xbfb8aa3b, v117
	v_rcp_f32_e32 v116, v116
	v_exp_f32_e32 v117, v117
	s_nop 0
	v_add_f32_e32 v117, 1.0, v117
	v_rcp_f32_e32 v129, v129
	v_mul_f32_e32 v114, 0xbfb8aa3b, v114
	v_exp_f32_e32 v114, v114
	s_nop 0
	v_add_f32_e32 v114, 1.0, v114
	v_cvt_pk_bf16_f32 v162, v149, v151
	v_cvt_pk_bf16_f32 v163, v128, v129
	v_mul_f32_e32 v126, 0xbfb8aa3b, v126
	v_rcp_f32_e32 v117, v117
	v_cvt_pk_bf16_f32 v164, v150, v152
	v_cvt_pk_bf16_f32 v165, v116, v117
	v_exp_f32_e32 v126, v126
	s_nop 0
	v_add_f32_e32 v126, 1.0, v126
	v_mul_f32_e32 v115, 0xbfb8aa3b, v115
	v_rcp_f32_e32 v114, v114
	v_exp_f32_e32 v115, v115
	s_nop 0
	v_add_f32_e32 v115, 1.0, v115
	v_mul_f32_e32 v127, 0xbfb8aa3b, v127
	v_exp_f32_e32 v127, v127
	v_rcp_f32_e32 v116, v126
	v_add_f32_e32 v127, 1.0, v127
	v_mul_f32_e32 v88, 0xbfb8aa3b, v88
	v_rcp_f32_e32 v115, v115
	v_exp_f32_e32 v88, v88
	s_nop 0
	v_add_f32_e32 v88, 1.0, v88
	v_mul_f32_e32 v86, 0xbfb8aa3b, v86
	v_exp_f32_e32 v86, v86
	v_rcp_f32_e32 v117, v127
	v_add_f32_e32 v86, 1.0, v86
	v_mul_f32_e32 v89, 0xbfb8aa3b, v89
	v_rcp_f32_e32 v88, v88
	v_exp_f32_e32 v89, v89
	s_nop 0
	v_add_f32_e32 v89, 1.0, v89
	v_mul_f32_e32 v87, 0xbfb8aa3b, v87
	v_rcp_f32_e32 v126, v86
	v_exp_f32_e32 v87, v87
	s_nop 0
	v_add_f32_e32 v87, 1.0, v87
	v_div_scale_f32 v128, s[34:35], v87, v87, 1.0
	v_rcp_f32_e32 v149, v128
	v_rcp_f32_e32 v89, v89
	v_lshl_add_u64 v[6:7], s[10:11], 0, v[6:7]
	v_fma_f32 v86, -v128, v149, 1.0
	v_fmac_f32_e32 v149, v86, v149
	v_lshl_add_u64 v[6:7], v[6:7], 0, v[34:35]
	global_store_dwordx4 v[6:7], v[162:165], off
	v_rcp_f32_e32 v127, v87
	v_cvt_pk_bf16_f32 v86, v114, v115
	v_mul_f32_e32 v114, 0xbfb8aa3b, v122
	v_exp_f32_e32 v114, v114
	v_cvt_pk_bf16_f32 v87, v88, v89
	v_cvt_pk_bf16_f32 v88, v116, v117
	v_cvt_pk_bf16_f32 v89, v126, v127
	global_store_dwordx4 v[6:7], v[86:89], off offset:256
	v_mul_f32_e32 v106, 0xbfb8aa3b, v106
	v_exp_f32_e32 v106, v106
	v_add_f32_e32 v88, 1.0, v114
	v_add_f32_e32 v106, 1.0, v106
	v_mul_f32_e32 v107, 0xbfb8aa3b, v107
	v_exp_f32_e32 v107, v107
	v_rcp_f32_e32 v88, v88
	v_mul_f32_e32 v116, 0xbfb8aa3b, v123
	v_exp_f32_e32 v116, v116
	s_nop 0
	v_add_f32_e32 v115, 1.0, v116
	v_rcp_f32_e32 v89, v106
	v_add_f32_e32 v107, 1.0, v107
	v_mul_f32_e32 v122, 0xbfb8aa3b, v124
	v_exp_f32_e32 v122, v122
	v_rcp_f32_e32 v106, v115
	v_add_f32_e32 v116, 1.0, v122
	v_mul_f32_e32 v108, 0xbfb8aa3b, v108
	v_exp_f32_e32 v108, v108
	v_rcp_f32_e32 v114, v107
	v_add_f32_e32 v108, 1.0, v108
	v_mul_f32_e32 v123, 0xbfb8aa3b, v125
	v_exp_f32_e32 v123, v123
	v_rcp_f32_e32 v107, v116
	v_add_f32_e32 v117, 1.0, v123
	v_mul_f32_e32 v109, 0xbfb8aa3b, v109
	v_exp_f32_e32 v109, v109
	v_rcp_f32_e32 v115, v108
	v_add_f32_e32 v109, 1.0, v109
	v_mul_f32_e32 v70, 0xbfb8aa3b, v70
	v_exp_f32_e32 v70, v70
	v_rcp_f32_e32 v108, v117
	v_add_f32_e32 v70, 1.0, v70
	v_cvt_pk_bf16_f32 v106, v88, v106
	v_rcp_f32_e32 v109, v109
	v_or_b32_e32 v86, 16, v148
	v_ashrrev_i32_e32 v87, 31, v86
	v_lshlrev_b64 v[86:87], 14, v[86:87]
	v_mul_f32_e32 v48, 0xbfb8aa3b, v48
	v_lshl_add_u64 v[86:87], s[10:11], 0, v[86:87]
	v_cvt_pk_bf16_f32 v107, v107, v108
	v_cvt_pk_bf16_f32 v108, v89, v114
	v_exp_f32_e32 v48, v48
	v_lshl_add_u64 v[86:87], v[86:87], 0, v[34:35]
	v_cvt_pk_bf16_f32 v109, v115, v109
	global_store_dwordx4 v[86:87], v[106:109], off
	v_add_f32_e32 v48, 1.0, v48
	v_mul_f32_e32 v71, 0xbfb8aa3b, v71
	v_rcp_f32_e32 v70, v70
	v_exp_f32_e32 v71, v71
	s_nop 0
	v_add_f32_e32 v71, 1.0, v71
	v_mul_f32_e32 v49, 0xbfb8aa3b, v49
	v_rcp_f32_e32 v48, v48
	v_exp_f32_e32 v49, v49
	s_nop 0
	v_add_f32_e32 v49, 1.0, v49
	v_mul_f32_e32 v72, 0xbfb8aa3b, v72
	v_rcp_f32_e32 v71, v71
	v_exp_f32_e32 v72, v72
	s_nop 0
	v_add_f32_e32 v72, 1.0, v72
	v_mul_f32_e32 v46, 0xbfb8aa3b, v46
	v_rcp_f32_e32 v49, v49
	v_exp_f32_e32 v46, v46
	s_nop 0
	v_add_f32_e32 v46, 1.0, v46
	v_mul_f32_e32 v73, 0xbfb8aa3b, v73
	v_rcp_f32_e32 v72, v72
	v_exp_f32_e32 v73, v73
	s_nop 0
	v_add_f32_e32 v73, 1.0, v73
	v_mul_f32_e32 v47, 0xbfb8aa3b, v47
	v_rcp_f32_e32 v88, v46
	v_exp_f32_e32 v47, v47
	s_nop 0
	v_add_f32_e32 v47, 1.0, v47
	v_rcp_f32_e32 v73, v73
	v_mul_f32_e32 v62, 0xbfb8aa3b, v62
	v_rcp_f32_e32 v89, v47
	v_cvt_pk_bf16_f32 v46, v70, v71
	v_mul_f32_e32 v70, 0xbfb8aa3b, v118
	v_exp_f32_e32 v70, v70
	v_cvt_pk_bf16_f32 v47, v72, v73
	v_cvt_pk_bf16_f32 v48, v48, v49
	v_cvt_pk_bf16_f32 v49, v88, v89
	global_store_dwordx4 v[86:87], v[46:49], off offset:256
	v_mul_f32_e32 v73, 0xbfb8aa3b, v102
	v_exp_f32_e32 v73, v73
	v_add_f32_e32 v48, 1.0, v70
	v_exp_f32_e32 v62, v62
	v_or_b32_e32 v46, 32, v148
	v_ashrrev_i32_e32 v47, 31, v46
	v_add_f32_e32 v71, 1.0, v73
	v_mul_f32_e32 v72, 0xbfb8aa3b, v119
	v_rcp_f32_e32 v48, v48
	v_exp_f32_e32 v72, v72
	s_nop 0
	v_add_f32_e32 v72, 1.0, v72
	v_mul_f32_e32 v86, 0xbfb8aa3b, v103
	v_exp_f32_e32 v86, v86
	v_rcp_f32_e32 v49, v71
	v_add_f32_e32 v73, 1.0, v86
	v_mul_f32_e32 v87, 0xbfb8aa3b, v120
	v_exp_f32_e32 v87, v87
	v_rcp_f32_e32 v70, v72
	v_add_f32_e32 v86, 1.0, v87
	v_rcp_f32_e32 v72, v73
	v_mul_f32_e32 v88, 0xbfb8aa3b, v104
	v_exp_f32_e32 v88, v88
	s_nop 0
	v_add_f32_e32 v87, 1.0, v88
	v_mul_f32_e32 v89, 0xbfb8aa3b, v121
	v_exp_f32_e32 v89, v89
	v_rcp_f32_e32 v71, v86
	v_add_f32_e32 v88, 1.0, v89
	v_mul_f32_e32 v102, 0xbfb8aa3b, v105
	v_exp_f32_e32 v102, v102
	v_rcp_f32_e32 v73, v87
	v_add_f32_e32 v89, 1.0, v102
	v_cvt_pk_bf16_f32 v70, v48, v70
	v_add_f32_e32 v48, 1.0, v62
	v_rcp_f32_e32 v86, v88
	s_nop 0
	v_cvt_pk_bf16_f32 v71, v71, v86
	v_lshlrev_b64 v[46:47], 14, v[46:47]
	v_mul_f32_e32 v44, 0xbfb8aa3b, v44
	v_lshl_add_u64 v[46:47], s[10:11], 0, v[46:47]
	v_cvt_pk_bf16_f32 v72, v49, v72
	v_exp_f32_e32 v44, v44
	v_lshl_add_u64 v[46:47], v[46:47], 0, v[34:35]
	v_rcp_f32_e32 v87, v89
	s_nop 0
	v_cvt_pk_bf16_f32 v73, v73, v87
	global_store_dwordx4 v[46:47], v[70:73], off
	v_add_f32_e32 v44, 1.0, v44
	v_mul_f32_e32 v63, 0xbfb8aa3b, v63
	v_rcp_f32_e32 v48, v48
	v_exp_f32_e32 v63, v63
	s_nop 0
	v_add_f32_e32 v62, 1.0, v63
	v_mul_f32_e32 v45, 0xbfb8aa3b, v45
	v_rcp_f32_e32 v44, v44
	v_exp_f32_e32 v45, v45
	s_nop 0
	v_add_f32_e32 v45, 1.0, v45
	v_rcp_f32_e32 v49, v62
	v_mul_f32_e32 v64, 0xbfb8aa3b, v64
	v_exp_f32_e32 v64, v64
	s_nop 0
	v_add_f32_e32 v63, 1.0, v64
	v_mul_f32_e32 v42, 0xbfb8aa3b, v42
	v_rcp_f32_e32 v45, v45
	v_exp_f32_e32 v42, v42
	s_nop 0
	v_add_f32_e32 v42, 1.0, v42
	v_rcp_f32_e32 v62, v63
	v_mul_f32_e32 v65, 0xbfb8aa3b, v65
	v_exp_f32_e32 v65, v65
	s_nop 0
	v_add_f32_e32 v64, 1.0, v65
	v_mul_f32_e32 v43, 0xbfb8aa3b, v43
	v_rcp_f32_e32 v63, v42
	v_exp_f32_e32 v43, v43
	s_nop 0
	v_add_f32_e32 v43, 1.0, v43
	v_rcp_f32_e32 v64, v64
	v_mul_f32_e32 v54, 0xbfb8aa3b, v54
	v_rcp_f32_e32 v65, v43
	v_cvt_pk_bf16_f32 v42, v48, v49
	v_mul_f32_e32 v48, 0xbfb8aa3b, v110
	v_exp_f32_e32 v48, v48
	v_cvt_pk_bf16_f32 v43, v62, v64
	v_cvt_pk_bf16_f32 v44, v44, v45
	v_cvt_pk_bf16_f32 v45, v63, v65
	global_store_dwordx4 v[46:47], v[42:45], off offset:256
	v_mul_f32_e32 v49, 0xbfb8aa3b, v98
	v_exp_f32_e32 v49, v49
	v_add_f32_e32 v44, 1.0, v48
	v_exp_f32_e32 v54, v54
	v_or_b32_e32 v42, 48, v148
	v_ashrrev_i32_e32 v43, 31, v42
	v_add_f32_e32 v47, 1.0, v49
	v_mul_f32_e32 v48, 0xbfb8aa3b, v111
	v_rcp_f32_e32 v44, v44
	v_exp_f32_e32 v48, v48
	s_nop 0
	v_add_f32_e32 v48, 1.0, v48
	v_rcp_f32_e32 v46, v47
	v_mul_f32_e32 v62, 0xbfb8aa3b, v99
	v_exp_f32_e32 v62, v62
	s_nop 0
	v_add_f32_e32 v49, 1.0, v62
	v_mul_f32_e32 v63, 0xbfb8aa3b, v112
	v_exp_f32_e32 v63, v63
	v_rcp_f32_e32 v45, v48
	v_add_f32_e32 v62, 1.0, v63
	v_mul_f32_e32 v64, 0xbfb8aa3b, v100
	v_exp_f32_e32 v64, v64
	v_rcp_f32_e32 v47, v49
	v_add_f32_e32 v63, 1.0, v64
	v_mul_f32_e32 v65, 0xbfb8aa3b, v113
	v_exp_f32_e32 v65, v65
	v_rcp_f32_e32 v48, v62
	v_add_f32_e32 v64, 1.0, v65
	v_mul_f32_e32 v70, 0xbfb8aa3b, v101
	v_exp_f32_e32 v70, v70
	v_rcp_f32_e32 v49, v63
	v_add_f32_e32 v65, 1.0, v70
	v_rcp_f32_e32 v62, v64
	v_cvt_pk_bf16_f32 v44, v44, v45
	v_cvt_pk_bf16_f32 v45, v48, v62
	v_add_f32_e32 v48, 1.0, v54
	v_lshlrev_b64 v[42:43], 14, v[42:43]
	v_lshl_add_u64 v[42:43], s[10:11], 0, v[42:43]
	v_mul_f32_e32 v36, 0xbfb8aa3b, v36
	v_lshl_add_u64 v[42:43], v[42:43], 0, v[34:35]
	v_exp_f32_e32 v36, v36
	v_rcp_f32_e32 v63, v65
	v_cvt_pk_bf16_f32 v46, v46, v47
	v_cvt_pk_bf16_f32 v47, v49, v63
	global_store_dwordx4 v[42:43], v[44:47], off
	v_add_f32_e32 v36, 1.0, v36
	v_mul_f32_e32 v49, 0xbfb8aa3b, v55
	v_exp_f32_e32 v49, v49
	v_rcp_f32_e32 v44, v48
	v_add_f32_e32 v46, 1.0, v49
	v_mul_f32_e32 v37, 0xbfb8aa3b, v37
	v_exp_f32_e32 v37, v37
	v_rcp_f32_e32 v36, v36
	v_add_f32_e32 v37, 1.0, v37
	v_rcp_f32_e32 v45, v46
	v_mul_f32_e32 v54, 0xbfb8aa3b, v56
	v_exp_f32_e32 v54, v54
	s_nop 0
	v_add_f32_e32 v48, 1.0, v54
	v_mul_f32_e32 v28, 0xbfb8aa3b, v28
	v_exp_f32_e32 v28, v28
	v_rcp_f32_e32 v37, v37
	v_add_f32_e32 v28, 1.0, v28
	v_mul_f32_e32 v55, 0xbfb8aa3b, v57
	v_exp_f32_e32 v55, v55
	v_rcp_f32_e32 v46, v48
	v_add_f32_e32 v49, 1.0, v55
	v_mul_f32_e32 v29, 0xbfb8aa3b, v29
	v_exp_f32_e32 v29, v29
	v_rcp_f32_e32 v28, v28
	v_add_f32_e32 v29, 1.0, v29
	v_rcp_f32_e32 v47, v49
	v_cvt_pk_bf16_f32 v44, v44, v45
	v_cvt_pk_bf16_f32 v45, v46, v47
	v_mul_f32_e32 v46, 0xbfb8aa3b, v94
	v_rcp_f32_e32 v29, v29
	v_exp_f32_e32 v48, v46
	v_cvt_pk_bf16_f32 v46, v36, v37
	v_cvt_pk_bf16_f32 v47, v28, v29
	global_store_dwordx4 v[42:43], v[44:47], off offset:256
	v_add_f32_e32 v36, 1.0, v48
	v_lshlrev_b64 v[28:29], 14, v[146:147]
	v_lshl_add_u64 v[28:29], s[10:11], 0, v[28:29]
	v_lshl_add_u64 v[28:29], v[28:29], 0, v[34:35]
	v_mul_f32_e32 v43, 0xbfb8aa3b, v78
	v_exp_f32_e32 v43, v43
	s_nop 0
	v_add_f32_e32 v37, 1.0, v43
	v_mul_f32_e32 v42, 0xbfb8aa3b, v95
	v_exp_f32_e32 v42, v42
	v_rcp_f32_e32 v34, v36
	v_add_f32_e32 v42, 1.0, v42
	v_rcp_f32_e32 v36, v37
	v_mul_f32_e32 v44, 0xbfb8aa3b, v79
	v_exp_f32_e32 v44, v44
	s_nop 0
	v_add_f32_e32 v43, 1.0, v44
	v_mul_f32_e32 v45, 0xbfb8aa3b, v96
	v_exp_f32_e32 v45, v45
	v_rcp_f32_e32 v35, v42
	v_add_f32_e32 v44, 1.0, v45
	v_mul_f32_e32 v46, 0xbfb8aa3b, v80
	v_exp_f32_e32 v46, v46
	v_rcp_f32_e32 v37, v43
	v_add_f32_e32 v45, 1.0, v46
	v_mul_f32_e32 v47, 0xbfb8aa3b, v97
	v_exp_f32_e32 v47, v47
	v_rcp_f32_e32 v42, v44
	v_add_f32_e32 v46, 1.0, v47
	v_mul_f32_e32 v48, 0xbfb8aa3b, v81
	v_exp_f32_e32 v48, v48
	v_rcp_f32_e32 v43, v45
	v_add_f32_e32 v47, 1.0, v48
	v_mul_f32_e32 v38, 0xbfb8aa3b, v38
	v_exp_f32_e32 v38, v38
	s_nop 0
	v_add_f32_e32 v38, 1.0, v38
	v_rcp_f32_e32 v44, v46
	v_cvt_pk_bf16_f32 v34, v34, v35
	v_cvt_pk_bf16_f32 v35, v42, v44
	v_mul_f32_e32 v26, 0xbfb8aa3b, v26
	v_exp_f32_e32 v26, v26
	v_rcp_f32_e32 v45, v47
	v_cvt_pk_bf16_f32 v36, v36, v37
	v_cvt_pk_bf16_f32 v37, v43, v45
	global_store_dwordx4 v[28:29], v[34:37], off
	v_add_f32_e32 v26, 1.0, v26
	v_mul_f32_e32 v39, 0xbfb8aa3b, v39
	v_exp_f32_e32 v39, v39
	v_rcp_f32_e32 v34, v38
	v_add_f32_e32 v36, 1.0, v39
	v_mul_f32_e32 v27, 0xbfb8aa3b, v27
	v_exp_f32_e32 v27, v27
	v_rcp_f32_e32 v26, v26
	v_add_f32_e32 v27, 1.0, v27
	v_rcp_f32_e32 v35, v36
	v_mul_f32_e32 v40, 0xbfb8aa3b, v40
	v_exp_f32_e32 v40, v40
	s_nop 0
	v_add_f32_e32 v38, 1.0, v40
	v_mul_f32_e32 v16, 0xbfb8aa3b, v16
	v_exp_f32_e32 v16, v16
	v_rcp_f32_e32 v27, v27
	v_add_f32_e32 v16, 1.0, v16
	v_mul_f32_e32 v41, 0xbfb8aa3b, v41
	v_exp_f32_e32 v41, v41
	v_rcp_f32_e32 v36, v38
	v_add_f32_e32 v39, 1.0, v41
	v_mul_f32_e32 v17, 0xbfb8aa3b, v17
	v_exp_f32_e32 v17, v17
	v_rcp_f32_e32 v16, v16
	v_add_f32_e32 v17, 1.0, v17
	v_rcp_f32_e32 v37, v39
	v_cvt_pk_bf16_f32 v34, v34, v35
	v_rcp_f32_e32 v17, v17
	v_mul_f32_e32 v38, 0xbfb8aa3b, v90
	v_exp_f32_e32 v38, v38
	v_cvt_pk_bf16_f32 v35, v36, v37
	v_cvt_pk_bf16_f32 v36, v26, v27
	v_cvt_pk_bf16_f32 v37, v16, v17
	global_store_dwordx4 v[28:29], v[34:37], off offset:256
	v_add_f32_e32 v26, 1.0, v38
	s_nop 1
	v_mul_f32_e32 v34, 0xbfb8aa3b, v66
	v_exp_f32_e32 v34, v34
	v_mul_f32_e32 v36, 0xbfb8aa3b, v91
	v_add_f32_e32 v28, 1.0, v34
	v_rcp_f32_e32 v26, v26
	v_exp_f32_e32 v36, v36
	s_nop 0
	v_add_f32_e32 v34, 1.0, v36
	v_mul_f32_e32 v35, 0xbfb8aa3b, v67
	v_rcp_f32_e32 v28, v28
	v_exp_f32_e32 v35, v35
	s_nop 0
	v_add_f32_e32 v35, 1.0, v35
	v_mul_f32_e32 v37, 0xbfb8aa3b, v92
	v_exp_f32_e32 v37, v37
	v_rcp_f32_e32 v27, v34
	v_add_f32_e32 v36, 1.0, v37
	v_mul_f32_e32 v38, 0xbfb8aa3b, v68
	v_exp_f32_e32 v38, v38
	v_rcp_f32_e32 v29, v35
	v_add_f32_e32 v37, 1.0, v38
	v_mul_f32_e32 v39, 0xbfb8aa3b, v93
	v_exp_f32_e32 v39, v39
	v_rcp_f32_e32 v34, v36
	v_add_f32_e32 v38, 1.0, v39
	v_mul_f32_e32 v40, 0xbfb8aa3b, v69
	v_exp_f32_e32 v40, v40
	v_rcp_f32_e32 v35, v37
	v_add_f32_e32 v39, 1.0, v40
	v_cvt_pk_bf16_f32 v26, v26, v27
	v_mul_f32_e32 v27, 0xbfb8aa3b, v30
	v_rcp_f32_e32 v36, v38
	v_exp_f32_e32 v30, v27
	s_nop 0
	v_add_f32_e32 v30, 1.0, v30
	v_rcp_f32_e32 v37, v39
	v_cvt_pk_bf16_f32 v27, v34, v36
	v_cvt_pk_bf16_f32 v28, v28, v29
	v_cvt_pk_bf16_f32 v29, v35, v37
	v_add_co_u32_e32 v34, vcc, s55, v6
	v_mul_f32_e32 v14, 0xbfb8aa3b, v14
	s_nop 0
	v_addc_co_u32_e32 v35, vcc, 0, v7, vcc
	v_exp_f32_e32 v14, v14
	global_store_dwordx4 v[34:35], v[26:29], off
	v_mul_f32_e32 v31, 0xbfb8aa3b, v31
	v_exp_f32_e32 v31, v31
	v_add_f32_e32 v14, 1.0, v14
	v_rcp_f32_e32 v26, v30
	v_add_f32_e32 v28, 1.0, v31
	v_mul_f32_e32 v15, 0xbfb8aa3b, v15
	v_exp_f32_e32 v15, v15
	v_rcp_f32_e32 v14, v14
	v_add_f32_e32 v15, 1.0, v15
	v_rcp_f32_e32 v27, v28
	v_mul_f32_e32 v32, 0xbfb8aa3b, v32
	v_exp_f32_e32 v32, v32
	s_nop 0
	v_add_f32_e32 v30, 1.0, v32
	v_mul_f32_e32 v12, 0xbfb8aa3b, v12
	v_exp_f32_e32 v12, v12
	v_rcp_f32_e32 v15, v15
	v_add_f32_e32 v12, 1.0, v12
	v_mul_f32_e32 v33, 0xbfb8aa3b, v33
	v_exp_f32_e32 v33, v33
	v_rcp_f32_e32 v28, v30
	v_add_f32_e32 v31, 1.0, v33
	v_mul_f32_e32 v13, 0xbfb8aa3b, v13
	v_exp_f32_e32 v13, v13
	v_rcp_f32_e32 v29, v12
	v_add_f32_e32 v13, 1.0, v13
	v_rcp_f32_e32 v30, v31
	v_lshl_add_u64 v[16:17], v[6:7], 0, s[16:17]
	v_rcp_f32_e32 v31, v13
	v_mul_f32_e32 v12, 0xbfb8aa3b, v82
	v_exp_f32_e32 v32, v12
	v_cvt_pk_bf16_f32 v12, v26, v27
	v_cvt_pk_bf16_f32 v13, v28, v30
	v_cvt_pk_bf16_f32 v14, v14, v15
	v_cvt_pk_bf16_f32 v15, v29, v31
	global_store_dwordx4 v[16:17], v[12:15], off offset:256
	v_add_f32_e32 v26, 1.0, v32
	s_nop 1
	v_mul_f32_e32 v16, 0xbfb8aa3b, v58
	v_exp_f32_e32 v16, v16
	v_pk_mul_f32 v[84:85], v[84:85], v[186:187]
	v_add_f32_e32 v16, 1.0, v16
	v_mul_f32_e32 v28, 0xbfb8aa3b, v83
	v_exp_f32_e32 v28, v28
	v_rcp_f32_e32 v14, v26
	v_add_f32_e32 v17, 1.0, v28
	v_mul_f32_e32 v27, 0xbfb8aa3b, v59
	v_rcp_f32_e32 v16, v16
	v_exp_f32_e32 v27, v27
	s_nop 0
	v_add_f32_e32 v27, 1.0, v27
	v_rcp_f32_e32 v15, v17
	v_mul_f32_e32 v29, 0xbfb8aa3b, v84
	v_exp_f32_e32 v29, v29
	s_nop 0
	v_add_f32_e32 v28, 1.0, v29
	v_mul_f32_e32 v30, 0xbfb8aa3b, v60
	v_exp_f32_e32 v30, v30
	v_rcp_f32_e32 v17, v27
	v_add_f32_e32 v29, 1.0, v30
	v_mul_f32_e32 v31, 0xbfb8aa3b, v85
	v_exp_f32_e32 v31, v31
	v_rcp_f32_e32 v26, v28
	v_add_f32_e32 v30, 1.0, v31
	v_mul_f32_e32 v32, 0xbfb8aa3b, v61
	v_exp_f32_e32 v32, v32
	v_rcp_f32_e32 v27, v29
	v_add_f32_e32 v31, 1.0, v32
	v_cvt_pk_bf16_f32 v14, v14, v15
	v_mul_f32_e32 v15, 0xbfb8aa3b, v22
	v_rcp_f32_e32 v28, v30
	v_exp_f32_e32 v22, v15
	s_nop 0
	v_add_f32_e32 v22, 1.0, v22
	v_rcp_f32_e32 v29, v31
	v_cvt_pk_bf16_f32 v15, v26, v28
	v_cvt_pk_bf16_f32 v16, v16, v17
	v_cvt_pk_bf16_f32 v17, v27, v29
	v_add_co_u32_e32 v26, vcc, s60, v6
	v_mul_f32_e32 v10, 0xbfb8aa3b, v10
	s_nop 0
	v_addc_co_u32_e32 v27, vcc, 0, v7, vcc
	v_exp_f32_e32 v10, v10
	global_store_dwordx4 v[26:27], v[14:17], off
	v_mul_f32_e32 v23, 0xbfb8aa3b, v23
	v_exp_f32_e32 v23, v23
	v_add_f32_e32 v10, 1.0, v10
	v_rcp_f32_e32 v14, v22
	v_add_f32_e32 v16, 1.0, v23
	v_mul_f32_e32 v11, 0xbfb8aa3b, v11
	v_exp_f32_e32 v11, v11
	v_rcp_f32_e32 v10, v10
	v_add_f32_e32 v11, 1.0, v11
	v_rcp_f32_e32 v15, v16
	v_mul_f32_e32 v24, 0xbfb8aa3b, v24
	v_exp_f32_e32 v24, v24
	s_nop 0
	v_add_f32_e32 v22, 1.0, v24
	v_mul_f32_e32 v8, 0xbfb8aa3b, v8
	v_exp_f32_e32 v8, v8
	v_rcp_f32_e32 v11, v11
	v_add_f32_e32 v8, 1.0, v8
	v_mul_f32_e32 v25, 0xbfb8aa3b, v25
	v_exp_f32_e32 v25, v25
	v_rcp_f32_e32 v16, v22
	v_add_f32_e32 v23, 1.0, v25
	v_mul_f32_e32 v9, 0xbfb8aa3b, v9
	v_exp_f32_e32 v9, v9
	v_rcp_f32_e32 v17, v8
	v_add_f32_e32 v9, 1.0, v9
	v_rcp_f32_e32 v22, v23
	v_lshl_add_u64 v[12:13], v[6:7], 0, s[18:19]
	v_rcp_f32_e32 v23, v9
	v_mul_f32_e32 v8, 0xbfb8aa3b, v74
	v_exp_f32_e32 v24, v8
	v_cvt_pk_bf16_f32 v8, v14, v15
	v_cvt_pk_bf16_f32 v9, v16, v22
	v_cvt_pk_bf16_f32 v10, v10, v11
	v_cvt_pk_bf16_f32 v11, v17, v23
	global_store_dwordx4 v[12:13], v[8:11], off offset:256
	v_add_f32_e32 v14, 1.0, v24
	s_nop 1
	v_mul_f32_e32 v12, 0xbfb8aa3b, v50
	v_exp_f32_e32 v12, v12
	v_lshl_add_u64 v[8:9], v[6:7], 0, s[20:21]
	v_add_f32_e32 v12, 1.0, v12
	v_mul_f32_e32 v16, 0xbfb8aa3b, v75
	v_exp_f32_e32 v16, v16
	v_rcp_f32_e32 v10, v14
	v_add_f32_e32 v13, 1.0, v16
	v_mul_f32_e32 v15, 0xbfb8aa3b, v51
	v_rcp_f32_e32 v12, v12
	v_exp_f32_e32 v15, v15
	s_nop 0
	v_add_f32_e32 v15, 1.0, v15
	v_rcp_f32_e32 v11, v13
	v_mul_f32_e32 v17, 0xbfb8aa3b, v76
	v_exp_f32_e32 v17, v17
	s_nop 0
	v_add_f32_e32 v16, 1.0, v17
	v_mul_f32_e32 v22, 0xbfb8aa3b, v52
	v_exp_f32_e32 v22, v22
	v_rcp_f32_e32 v13, v15
	v_add_f32_e32 v17, 1.0, v22
	v_mul_f32_e32 v23, 0xbfb8aa3b, v77
	v_exp_f32_e32 v23, v23
	v_rcp_f32_e32 v14, v16
	v_add_f32_e32 v22, 1.0, v23
	v_mul_f32_e32 v24, 0xbfb8aa3b, v53
	v_exp_f32_e32 v24, v24
	v_rcp_f32_e32 v15, v17
	v_add_f32_e32 v23, 1.0, v24
	v_cvt_pk_bf16_f32 v10, v10, v11
	v_mul_f32_e32 v11, 0xbfb8aa3b, v18
	v_rcp_f32_e32 v16, v22
	v_exp_f32_e32 v18, v11
	v_cvt_pk_bf16_f32 v11, v14, v16
	v_add_f32_e32 v14, 1.0, v18
	v_rcp_f32_e32 v17, v23
	v_cvt_pk_bf16_f32 v12, v12, v13
	v_cvt_pk_bf16_f32 v13, v15, v17
	v_add_co_u32_e32 v6, vcc, s61, v6
	v_mul_f32_e32 v2, 0xbfb8aa3b, v2
	s_nop 0
	v_addc_co_u32_e32 v7, vcc, 0, v7, vcc
	v_exp_f32_e32 v2, v2
	global_store_dwordx4 v[6:7], v[10:13], off
	v_add_f32_e32 v2, 1.0, v2
	s_nop 1
	v_mul_f32_e32 v13, 0xbfb8aa3b, v19
	v_exp_f32_e32 v13, v13
	v_rcp_f32_e32 v6, v14
	v_add_f32_e32 v10, 1.0, v13
	v_mul_f32_e32 v3, 0xbfb8aa3b, v3
	v_exp_f32_e32 v3, v3
	v_rcp_f32_e32 v7, v2
	v_add_f32_e32 v3, 1.0, v3
	v_rcp_f32_e32 v2, v10
	v_mul_f32_e32 v14, 0xbfb8aa3b, v20
	v_exp_f32_e32 v14, v14
	s_nop 0
	v_add_f32_e32 v12, 1.0, v14
	v_mul_f32_e32 v4, 0xbfb8aa3b, v4
	v_exp_f32_e32 v4, v4
	v_rcp_f32_e32 v10, v3
	v_add_f32_e32 v4, 1.0, v4
	v_mul_f32_e32 v15, 0xbfb8aa3b, v21
	v_exp_f32_e32 v15, v15
	v_rcp_f32_e32 v3, v12
	v_add_f32_e32 v13, 1.0, v15
	v_mul_f32_e32 v5, 0xbfb8aa3b, v5
	v_exp_f32_e32 v5, v5
	v_rcp_f32_e32 v11, v4
	v_add_f32_e32 v5, 1.0, v5
	v_rcp_f32_e32 v4, v13
	v_cvt_pk_bf16_f32 v2, v6, v2
	v_rcp_f32_e32 v5, v5
	s_andn2_b64 vcc, exec, s[4:5]
	s_mov_b64 s[4:5], -1
	v_cvt_pk_bf16_f32 v3, v3, v4
	v_cvt_pk_bf16_f32 v4, v7, v10
	v_cvt_pk_bf16_f32 v5, v11, v5
	global_store_dwordx4 v[8:9], v[2:5], off offset:256
	s_cbranch_vccnz .LBB0_1474
	s_andn2_b64 vcc, exec, s[0:1]
	s_cbranch_vccnz .LBB0_1473
	s_barrier
	s_branch .LBB0_1473
